# stack + accumulator zeroing between GEMM units via packed 2-register moves (64 instead of 128 VALU)
# speedup vs baseline: 1.0194x; 1.0120x over previous
; template <class Epi, class SchedT, bool ALIGN_EPI, bool SP2, bool FP8 = false>
; __device__ __forceinline__ void gemm_phase(LAS unsigned char* lds, const Gemm g, const SchedT& S, const Epi& E, const int wid) {
;     ...
;         const bool has_next = S.next(ui + 1, nxt);
;         const char* nA = has_next ? (const char*)g.A + (size_t)nxt.pm * tstepA + (size_t)nxt.aoff * 2 : cA; const char* nB = has_next ? (const char*)g.Bt + (size_t)nxt.pn * tstepB + (size_t)nxt.boff * 2 : cB;
;         const int nt = cur.nt;
;         for (int t = 0; t < nt; t += 2) {
;             const bool last = (t == nt - 2);
;             const char* a1 = cA + (size_t)(t + 1) * kstep;
;             const char* a2 = last ? nA : cA + (size_t)(t + 2) * kstep; const char* b2 = last ? nB : cB + (size_t)(t + 2) * kstep;
;             const char* a3 = a2 + kstep; const char* b3 = b2 + kstep;
;     ...
; #pragma unroll
;         for (int a = 0; a < 2; ++a)
; #pragma unroll
;             for (int b = 0; b < 2; ++b)
; #pragma unroll
;                 for (int m = 0; m < 4; ++m)
; #pragma unroll
;                     for (int n = 0; n < 2; ++n) acc[a][b][m][n] = (f32x4){0.f, 0.f, 0.f, 0.f};
.LBB0_237:
	s_ashr_i32 s47, s46, 31
	s_lshl_b64 s[8:9], s[46:47], 18
	s_add_u32 s50, s4, s8
	s_addc_u32 s51, s5, s9
	s_cmp_lt_i32 s22, 1
	s_cbranch_scc1 .LBB0_245
	s_and_b64 s[8:9], s[68:69], exec
	s_cselect_b32 s8, s51, s67
	s_cselect_b32 s9, s50, s66
	s_add_i32 s20, s22, -2
	s_add_u32 s52, s52, 0x90080
	s_addc_u32 s53, s53, 0
	s_add_u32 s21, s66, 0x100
	v_mov_b32_e32 v0, 0
	s_addc_u32 s24, s67, 0
	s_mov_b32 s31, 0
	v_mov_b32_e32 v1, v0
	v_pk_mov_b32 v[2:3], v[0:1], v[0:1]
	v_pk_mov_b32 v[4:5], v[0:1], v[0:1]
	v_pk_mov_b32 v[6:7], v[0:1], v[0:1]
	v_pk_mov_b32 v[8:9], v[0:1], v[0:1]
	v_pk_mov_b32 v[10:11], v[0:1], v[0:1]
	v_pk_mov_b32 v[12:13], v[0:1], v[0:1]
	v_pk_mov_b32 v[14:15], v[0:1], v[0:1]
	v_pk_mov_b32 v[16:17], v[0:1], v[0:1]
	v_pk_mov_b32 v[18:19], v[0:1], v[0:1]
	v_pk_mov_b32 v[20:21], v[0:1], v[0:1]
	v_pk_mov_b32 v[22:23], v[0:1], v[0:1]
	v_pk_mov_b32 v[24:25], v[0:1], v[0:1]
	v_pk_mov_b32 v[26:27], v[0:1], v[0:1]
	v_pk_mov_b32 v[28:29], v[0:1], v[0:1]
	v_pk_mov_b32 v[30:31], v[0:1], v[0:1]
	v_pk_mov_b32 v[32:33], v[0:1], v[0:1]
	v_pk_mov_b32 v[34:35], v[0:1], v[0:1]
	v_pk_mov_b32 v[36:37], v[0:1], v[0:1]
	v_pk_mov_b32 v[38:39], v[0:1], v[0:1]
	v_pk_mov_b32 v[40:41], v[0:1], v[0:1]
	v_pk_mov_b32 v[42:43], v[0:1], v[0:1]
	v_pk_mov_b32 v[44:45], v[0:1], v[0:1]
	v_pk_mov_b32 v[46:47], v[0:1], v[0:1]
	v_pk_mov_b32 v[48:49], v[0:1], v[0:1]
	v_pk_mov_b32 v[50:51], v[0:1], v[0:1]
	v_pk_mov_b32 v[52:53], v[0:1], v[0:1]
	v_pk_mov_b32 v[54:55], v[0:1], v[0:1]
	v_pk_mov_b32 v[56:57], v[0:1], v[0:1]
	v_pk_mov_b32 v[58:59], v[0:1], v[0:1]
	v_pk_mov_b32 v[60:61], v[0:1], v[0:1]
	v_pk_mov_b32 v[62:63], v[0:1], v[0:1]
	v_pk_mov_b32 v[64:65], v[0:1], v[0:1]
	v_pk_mov_b32 v[66:67], v[0:1], v[0:1]
	v_pk_mov_b32 v[68:69], v[0:1], v[0:1]
	v_pk_mov_b32 v[70:71], v[0:1], v[0:1]
	v_pk_mov_b32 v[72:73], v[0:1], v[0:1]
	v_pk_mov_b32 v[74:75], v[0:1], v[0:1]
	v_pk_mov_b32 v[76:77], v[0:1], v[0:1]
	v_pk_mov_b32 v[78:79], v[0:1], v[0:1]
	v_pk_mov_b32 v[80:81], v[0:1], v[0:1]
	v_pk_mov_b32 v[82:83], v[0:1], v[0:1]
	v_pk_mov_b32 v[84:85], v[0:1], v[0:1]
	v_pk_mov_b32 v[86:87], v[0:1], v[0:1]
	v_pk_mov_b32 v[88:89], v[0:1], v[0:1]
	v_pk_mov_b32 v[90:91], v[0:1], v[0:1]
	v_pk_mov_b32 v[92:93], v[0:1], v[0:1]
	v_pk_mov_b32 v[94:95], v[0:1], v[0:1]
	v_pk_mov_b32 v[96:97], v[0:1], v[0:1]
	v_pk_mov_b32 v[98:99], v[0:1], v[0:1]
	v_pk_mov_b32 v[100:101], v[0:1], v[0:1]
	v_pk_mov_b32 v[102:103], v[0:1], v[0:1]
	v_pk_mov_b32 v[104:105], v[0:1], v[0:1]
	v_pk_mov_b32 v[106:107], v[0:1], v[0:1]
	v_pk_mov_b32 v[108:109], v[0:1], v[0:1]
	v_pk_mov_b32 v[110:111], v[0:1], v[0:1]
	v_pk_mov_b32 v[112:113], v[0:1], v[0:1]
	v_pk_mov_b32 v[114:115], v[0:1], v[0:1]
	v_pk_mov_b32 v[116:117], v[0:1], v[0:1]
	v_pk_mov_b32 v[118:119], v[0:1], v[0:1]
	v_pk_mov_b32 v[120:121], v[0:1], v[0:1]
	v_pk_mov_b32 v[122:123], v[0:1], v[0:1]
	v_pk_mov_b32 v[124:125], v[0:1], v[0:1]
	v_pk_mov_b32 v[126:127], v[0:1], v[0:1]

; template <class Epi, class SchedT, bool ALIGN_EPI, bool SP2, bool FP8 = false>
; __device__ __forceinline__ void gemm_phase(LAS unsigned char* lds, const Gemm g, const SchedT& S, const Epi& E, const int wid) {
;     ...
;         const bool has_next = S.next(ui + 1, nxt);
;         const char* nA = has_next ? (const char*)g.A + (size_t)nxt.pm * tstepA + (size_t)nxt.aoff * 2 : cA; const char* nB = has_next ? (const char*)g.Bt + (size_t)nxt.pn * tstepB + (size_t)nxt.boff * 2 : cB;
;         const int nt = cur.nt;
;         for (int t = 0; t < nt; t += 2) {
;             const bool last = (t == nt - 2);
;             const char* a1 = cA + (size_t)(t + 1) * kstep;
;             const char* a2 = last ? nA : cA + (size_t)(t + 2) * kstep; const char* b2 = last ? nB : cB + (size_t)(t + 2) * kstep;
;             const char* a3 = a2 + kstep; const char* b3 = b2 + kstep;
;     ...
; #pragma unroll
;         for (int a = 0; a < 2; ++a)
; #pragma unroll
;             for (int b = 0; b < 2; ++b)
; #pragma unroll
;                 for (int m = 0; m < 4; ++m)
; #pragma unroll
;                     for (int n = 0; n < 2; ++n) acc[a][b][m][n] = (f32x4){0.f, 0.f, 0.f, 0.f};
.LBB0_254:
	s_ashr_i32 s45, s44, 31
	s_lshl_b64 s[20:21], s[44:45], 19
	s_add_u32 s46, s23, s20
	s_addc_u32 s47, s34, s21
	s_ashr_i32 s43, s42, 31
	s_lshl_b64 s[20:21], s[42:43], 19
	s_add_u32 s48, s64, s20
	s_addc_u32 s49, s65, s21
	s_cmp_lt_i32 s8, 1
	s_cbranch_scc1 .LBB0_262
	s_and_b64 s[20:21], s[4:5], exec
	s_cselect_b32 s9, s47, s51
	s_cselect_b32 s20, s46, s50
	s_cselect_b32 s21, s49, s53
	s_cselect_b32 s24, s48, s52
	s_add_i32 s30, s8, -2
	s_add_u32 s50, s50, 0x40080
	s_addc_u32 s51, s51, 0
	s_add_u32 s31, s52, 0x100
	v_mov_b32_e32 v0, 0
	s_addc_u32 s38, s53, 0
	s_mov_b32 s39, 0
	v_mov_b32_e32 v1, v0
	v_pk_mov_b32 v[2:3], v[0:1], v[0:1]
	v_pk_mov_b32 v[4:5], v[0:1], v[0:1]
	v_pk_mov_b32 v[6:7], v[0:1], v[0:1]
	v_pk_mov_b32 v[8:9], v[0:1], v[0:1]
	v_pk_mov_b32 v[10:11], v[0:1], v[0:1]
	v_pk_mov_b32 v[12:13], v[0:1], v[0:1]
	v_pk_mov_b32 v[14:15], v[0:1], v[0:1]
	v_pk_mov_b32 v[16:17], v[0:1], v[0:1]
	v_pk_mov_b32 v[18:19], v[0:1], v[0:1]
	v_pk_mov_b32 v[20:21], v[0:1], v[0:1]
	v_pk_mov_b32 v[22:23], v[0:1], v[0:1]
	v_pk_mov_b32 v[24:25], v[0:1], v[0:1]
	v_pk_mov_b32 v[26:27], v[0:1], v[0:1]
	v_pk_mov_b32 v[28:29], v[0:1], v[0:1]
	v_pk_mov_b32 v[30:31], v[0:1], v[0:1]
	v_pk_mov_b32 v[32:33], v[0:1], v[0:1]
	v_pk_mov_b32 v[34:35], v[0:1], v[0:1]
	v_pk_mov_b32 v[36:37], v[0:1], v[0:1]
	v_pk_mov_b32 v[38:39], v[0:1], v[0:1]
	v_pk_mov_b32 v[40:41], v[0:1], v[0:1]
	v_pk_mov_b32 v[42:43], v[0:1], v[0:1]
	v_pk_mov_b32 v[44:45], v[0:1], v[0:1]
	v_pk_mov_b32 v[46:47], v[0:1], v[0:1]
	v_pk_mov_b32 v[48:49], v[0:1], v[0:1]
	v_pk_mov_b32 v[50:51], v[0:1], v[0:1]
	v_pk_mov_b32 v[52:53], v[0:1], v[0:1]
	v_pk_mov_b32 v[54:55], v[0:1], v[0:1]
	v_pk_mov_b32 v[56:57], v[0:1], v[0:1]
	v_pk_mov_b32 v[58:59], v[0:1], v[0:1]
	v_pk_mov_b32 v[60:61], v[0:1], v[0:1]
	v_pk_mov_b32 v[62:63], v[0:1], v[0:1]
	v_pk_mov_b32 v[64:65], v[0:1], v[0:1]
	v_pk_mov_b32 v[66:67], v[0:1], v[0:1]
	v_pk_mov_b32 v[68:69], v[0:1], v[0:1]
	v_pk_mov_b32 v[70:71], v[0:1], v[0:1]
	v_pk_mov_b32 v[72:73], v[0:1], v[0:1]
	v_pk_mov_b32 v[74:75], v[0:1], v[0:1]
	v_pk_mov_b32 v[76:77], v[0:1], v[0:1]
	v_pk_mov_b32 v[78:79], v[0:1], v[0:1]
	v_pk_mov_b32 v[80:81], v[0:1], v[0:1]
	v_pk_mov_b32 v[82:83], v[0:1], v[0:1]
	v_pk_mov_b32 v[84:85], v[0:1], v[0:1]
	v_pk_mov_b32 v[86:87], v[0:1], v[0:1]
	v_pk_mov_b32 v[88:89], v[0:1], v[0:1]
	v_pk_mov_b32 v[90:91], v[0:1], v[0:1]
	v_pk_mov_b32 v[92:93], v[0:1], v[0:1]
	v_pk_mov_b32 v[94:95], v[0:1], v[0:1]
	v_pk_mov_b32 v[96:97], v[0:1], v[0:1]
	v_pk_mov_b32 v[98:99], v[0:1], v[0:1]
	v_pk_mov_b32 v[100:101], v[0:1], v[0:1]
	v_pk_mov_b32 v[102:103], v[0:1], v[0:1]
	v_pk_mov_b32 v[104:105], v[0:1], v[0:1]
	v_pk_mov_b32 v[106:107], v[0:1], v[0:1]
	v_pk_mov_b32 v[108:109], v[0:1], v[0:1]
	v_pk_mov_b32 v[110:111], v[0:1], v[0:1]
	v_pk_mov_b32 v[112:113], v[0:1], v[0:1]
	v_pk_mov_b32 v[114:115], v[0:1], v[0:1]
	v_pk_mov_b32 v[116:117], v[0:1], v[0:1]
	v_pk_mov_b32 v[118:119], v[0:1], v[0:1]
	v_pk_mov_b32 v[120:121], v[0:1], v[0:1]
	v_pk_mov_b32 v[122:123], v[0:1], v[0:1]
	v_pk_mov_b32 v[124:125], v[0:1], v[0:1]
	v_pk_mov_b32 v[126:127], v[0:1], v[0:1]

; template <class Epi, class SchedT, bool ALIGN_EPI, bool SP2, bool FP8 = false>
; __device__ __forceinline__ void gemm_phase(LAS unsigned char* lds, const Gemm g, const SchedT& S, const Epi& E, const int wid) {
;     ...
;         const bool has_next = S.next(ui + 1, nxt);
;         const char* nA = has_next ? (const char*)g.A + (size_t)nxt.pm * tstepA + (size_t)nxt.aoff * 2 : cA; const char* nB = has_next ? (const char*)g.Bt + (size_t)nxt.pn * tstepB + (size_t)nxt.boff * 2 : cB;
;         const int nt = cur.nt;
;         for (int t = 0; t < nt; t += 2) {
;             const bool last = (t == nt - 2);
;             const char* a1 = cA + (size_t)(t + 1) * kstep;
;             const char* a2 = last ? nA : cA + (size_t)(t + 2) * kstep; const char* b2 = last ? nB : cB + (size_t)(t + 2) * kstep;
;             const char* a3 = a2 + kstep; const char* b3 = b2 + kstep;
;     ...
; #pragma unroll
;         for (int a = 0; a < 2; ++a)
; #pragma unroll
;             for (int b = 0; b < 2; ++b)
; #pragma unroll
;                 for (int m = 0; m < 4; ++m)
; #pragma unroll
;                     for (int n = 0; n < 2; ++n) acc[a][b][m][n] = (f32x4){0.f, 0.f, 0.f, 0.f};
.LBB0_538:
	s_add_i32 s20, s71, -2
	s_add_u32 s8, s66, 0x90080
	s_addc_u32 s9, s67, 0
	s_add_u32 s21, s10, 0x100
	v_mov_b32_e32 v0, 0
	s_addc_u32 s24, s11, 0
	s_mov_b32 s10, 0
	v_mov_b32_e32 v1, v0
	v_pk_mov_b32 v[2:3], v[0:1], v[0:1]
	v_pk_mov_b32 v[4:5], v[0:1], v[0:1]
	v_pk_mov_b32 v[6:7], v[0:1], v[0:1]
	v_pk_mov_b32 v[8:9], v[0:1], v[0:1]
	v_pk_mov_b32 v[10:11], v[0:1], v[0:1]
	v_pk_mov_b32 v[12:13], v[0:1], v[0:1]
	v_pk_mov_b32 v[14:15], v[0:1], v[0:1]
	v_pk_mov_b32 v[16:17], v[0:1], v[0:1]
	v_pk_mov_b32 v[18:19], v[0:1], v[0:1]
	v_pk_mov_b32 v[20:21], v[0:1], v[0:1]
	v_pk_mov_b32 v[22:23], v[0:1], v[0:1]
	v_pk_mov_b32 v[24:25], v[0:1], v[0:1]
	v_pk_mov_b32 v[26:27], v[0:1], v[0:1]
	v_pk_mov_b32 v[28:29], v[0:1], v[0:1]
	v_pk_mov_b32 v[30:31], v[0:1], v[0:1]
	v_pk_mov_b32 v[32:33], v[0:1], v[0:1]
	v_pk_mov_b32 v[34:35], v[0:1], v[0:1]
	v_pk_mov_b32 v[36:37], v[0:1], v[0:1]
	v_pk_mov_b32 v[38:39], v[0:1], v[0:1]
	v_pk_mov_b32 v[40:41], v[0:1], v[0:1]
	v_pk_mov_b32 v[42:43], v[0:1], v[0:1]
	v_pk_mov_b32 v[44:45], v[0:1], v[0:1]
	v_pk_mov_b32 v[46:47], v[0:1], v[0:1]
	v_pk_mov_b32 v[48:49], v[0:1], v[0:1]
	v_pk_mov_b32 v[50:51], v[0:1], v[0:1]
	v_pk_mov_b32 v[52:53], v[0:1], v[0:1]
	v_pk_mov_b32 v[54:55], v[0:1], v[0:1]
	v_pk_mov_b32 v[56:57], v[0:1], v[0:1]
	v_pk_mov_b32 v[58:59], v[0:1], v[0:1]
	v_pk_mov_b32 v[60:61], v[0:1], v[0:1]
	v_pk_mov_b32 v[62:63], v[0:1], v[0:1]
	v_pk_mov_b32 v[64:65], v[0:1], v[0:1]
	v_pk_mov_b32 v[66:67], v[0:1], v[0:1]
	v_pk_mov_b32 v[68:69], v[0:1], v[0:1]
	v_pk_mov_b32 v[70:71], v[0:1], v[0:1]
	v_pk_mov_b32 v[72:73], v[0:1], v[0:1]
	v_pk_mov_b32 v[74:75], v[0:1], v[0:1]
	v_pk_mov_b32 v[76:77], v[0:1], v[0:1]
	v_pk_mov_b32 v[78:79], v[0:1], v[0:1]
	v_pk_mov_b32 v[80:81], v[0:1], v[0:1]
	v_pk_mov_b32 v[82:83], v[0:1], v[0:1]
	v_pk_mov_b32 v[84:85], v[0:1], v[0:1]
	v_pk_mov_b32 v[86:87], v[0:1], v[0:1]
	v_pk_mov_b32 v[88:89], v[0:1], v[0:1]
	v_pk_mov_b32 v[90:91], v[0:1], v[0:1]
	v_pk_mov_b32 v[92:93], v[0:1], v[0:1]
	v_pk_mov_b32 v[94:95], v[0:1], v[0:1]
	v_pk_mov_b32 v[96:97], v[0:1], v[0:1]
	v_pk_mov_b32 v[98:99], v[0:1], v[0:1]
	v_pk_mov_b32 v[100:101], v[0:1], v[0:1]
	v_pk_mov_b32 v[102:103], v[0:1], v[0:1]
	v_pk_mov_b32 v[104:105], v[0:1], v[0:1]
	v_pk_mov_b32 v[106:107], v[0:1], v[0:1]
	v_pk_mov_b32 v[108:109], v[0:1], v[0:1]
	v_pk_mov_b32 v[110:111], v[0:1], v[0:1]
	v_pk_mov_b32 v[112:113], v[0:1], v[0:1]
	v_pk_mov_b32 v[114:115], v[0:1], v[0:1]
	v_pk_mov_b32 v[116:117], v[0:1], v[0:1]
	v_pk_mov_b32 v[118:119], v[0:1], v[0:1]
	v_pk_mov_b32 v[120:121], v[0:1], v[0:1]
	v_pk_mov_b32 v[122:123], v[0:1], v[0:1]
	v_pk_mov_b32 v[124:125], v[0:1], v[0:1]
	v_pk_mov_b32 v[126:127], v[0:1], v[0:1]

; template <class Epi, class SchedT, bool ALIGN_EPI, bool SP2, bool FP8 = false>
; __device__ __forceinline__ void gemm_phase(LAS unsigned char* lds, const Gemm g, const SchedT& S, const Epi& E, const int wid) {
;     ...
;         const bool has_next = S.next(ui + 1, nxt);
;         const char* nA = has_next ? (const char*)g.A + (size_t)nxt.pm * tstepA + (size_t)nxt.aoff * 2 : cA; const char* nB = has_next ? (const char*)g.Bt + (size_t)nxt.pn * tstepB + (size_t)nxt.boff * 2 : cB;
;         const int nt = cur.nt;
;         for (int t = 0; t < nt; t += 2) {
;             const bool last = (t == nt - 2);
;             const char* a1 = cA + (size_t)(t + 1) * kstep;
;             const char* a2 = last ? nA : cA + (size_t)(t + 2) * kstep; const char* b2 = last ? nB : cB + (size_t)(t + 2) * kstep;
;             const char* a3 = a2 + kstep; const char* b3 = b2 + kstep;
;     ...
; #pragma unroll
;         for (int a = 0; a < 2; ++a)
; #pragma unroll
;             for (int b = 0; b < 2; ++b)
; #pragma unroll
;                 for (int m = 0; m < 4; ++m)
; #pragma unroll
;                     for (int n = 0; n < 2; ++n) acc[a][b][m][n] = (f32x4){0.f, 0.f, 0.f, 0.f};
.LBB0_777:
	s_ashr_i32 s47, s46, 31
	s_lshl_b64 s[22:23], s[46:47], 18
	s_add_u32 s48, s36, s22
	s_addc_u32 s49, s37, s23
	s_ashr_i32 s45, s44, 31
	s_lshl_b64 s[22:23], s[44:45], 18
	s_add_u32 s50, s12, s22
	s_addc_u32 s51, s13, s23
	s_cmp_lt_i32 s20, 1
	s_cbranch_scc1 .LBB0_833
	s_and_b64 s[22:23], s[6:7], exec
	s_cselect_b32 s9, s49, s53
	s_cselect_b32 s21, s48, s52
	s_cselect_b32 s22, s51, s65
	s_cselect_b32 s23, s50, s64
	s_add_i32 s24, s20, -2
	s_add_u32 s52, s52, 0x20080
	s_addc_u32 s53, s53, 0
	s_add_u32 s30, s64, 0x100
	v_mov_b32_e32 v0, 0
	s_addc_u32 s31, s65, 0
	s_mov_b32 s47, 0
	s_waitcnt lgkmcnt(0)
	v_mov_b32_e32 v1, v0
	v_pk_mov_b32 v[2:3], v[0:1], v[0:1]
	v_pk_mov_b32 v[4:5], v[0:1], v[0:1]
	v_pk_mov_b32 v[6:7], v[0:1], v[0:1]
	v_pk_mov_b32 v[8:9], v[0:1], v[0:1]
	v_pk_mov_b32 v[10:11], v[0:1], v[0:1]
	v_pk_mov_b32 v[12:13], v[0:1], v[0:1]
	v_pk_mov_b32 v[14:15], v[0:1], v[0:1]
	v_pk_mov_b32 v[16:17], v[0:1], v[0:1]
	v_pk_mov_b32 v[18:19], v[0:1], v[0:1]
	v_pk_mov_b32 v[20:21], v[0:1], v[0:1]
	v_pk_mov_b32 v[22:23], v[0:1], v[0:1]
	v_pk_mov_b32 v[24:25], v[0:1], v[0:1]
	v_pk_mov_b32 v[26:27], v[0:1], v[0:1]
	v_pk_mov_b32 v[28:29], v[0:1], v[0:1]
	v_pk_mov_b32 v[30:31], v[0:1], v[0:1]
	v_pk_mov_b32 v[32:33], v[0:1], v[0:1]
	v_pk_mov_b32 v[34:35], v[0:1], v[0:1]
	v_pk_mov_b32 v[36:37], v[0:1], v[0:1]
	v_pk_mov_b32 v[38:39], v[0:1], v[0:1]
	v_pk_mov_b32 v[40:41], v[0:1], v[0:1]
	v_pk_mov_b32 v[42:43], v[0:1], v[0:1]
	v_pk_mov_b32 v[44:45], v[0:1], v[0:1]
	v_pk_mov_b32 v[46:47], v[0:1], v[0:1]
	v_pk_mov_b32 v[48:49], v[0:1], v[0:1]
	v_pk_mov_b32 v[50:51], v[0:1], v[0:1]
	v_pk_mov_b32 v[52:53], v[0:1], v[0:1]
	v_pk_mov_b32 v[54:55], v[0:1], v[0:1]
	v_pk_mov_b32 v[56:57], v[0:1], v[0:1]
	v_pk_mov_b32 v[58:59], v[0:1], v[0:1]
	v_pk_mov_b32 v[60:61], v[0:1], v[0:1]
	v_pk_mov_b32 v[62:63], v[0:1], v[0:1]
	v_pk_mov_b32 v[64:65], v[0:1], v[0:1]
	v_pk_mov_b32 v[66:67], v[0:1], v[0:1]
	v_pk_mov_b32 v[68:69], v[0:1], v[0:1]
	v_pk_mov_b32 v[70:71], v[0:1], v[0:1]
	v_pk_mov_b32 v[72:73], v[0:1], v[0:1]
	v_pk_mov_b32 v[74:75], v[0:1], v[0:1]
	v_pk_mov_b32 v[76:77], v[0:1], v[0:1]
	v_pk_mov_b32 v[78:79], v[0:1], v[0:1]
	v_pk_mov_b32 v[80:81], v[0:1], v[0:1]
	v_pk_mov_b32 v[82:83], v[0:1], v[0:1]
	v_pk_mov_b32 v[84:85], v[0:1], v[0:1]
	v_pk_mov_b32 v[86:87], v[0:1], v[0:1]
	v_pk_mov_b32 v[88:89], v[0:1], v[0:1]
	v_pk_mov_b32 v[90:91], v[0:1], v[0:1]
	v_pk_mov_b32 v[92:93], v[0:1], v[0:1]
	v_pk_mov_b32 v[94:95], v[0:1], v[0:1]
	v_pk_mov_b32 v[96:97], v[0:1], v[0:1]
	v_pk_mov_b32 v[98:99], v[0:1], v[0:1]
	v_pk_mov_b32 v[100:101], v[0:1], v[0:1]
	v_pk_mov_b32 v[102:103], v[0:1], v[0:1]
	v_pk_mov_b32 v[104:105], v[0:1], v[0:1]
	v_pk_mov_b32 v[106:107], v[0:1], v[0:1]
	v_pk_mov_b32 v[108:109], v[0:1], v[0:1]
	v_pk_mov_b32 v[110:111], v[0:1], v[0:1]
	v_pk_mov_b32 v[112:113], v[0:1], v[0:1]
	v_pk_mov_b32 v[114:115], v[0:1], v[0:1]
	v_pk_mov_b32 v[116:117], v[0:1], v[0:1]
	v_pk_mov_b32 v[118:119], v[0:1], v[0:1]
	v_pk_mov_b32 v[120:121], v[0:1], v[0:1]
	v_pk_mov_b32 v[122:123], v[0:1], v[0:1]
	v_pk_mov_b32 v[124:125], v[0:1], v[0:1]
	v_pk_mov_b32 v[126:127], v[0:1], v[0:1]

; template <class Epi, class SchedT, bool ALIGN_EPI, bool SP2, bool FP8 = false>
; __device__ __forceinline__ void gemm_phase(LAS unsigned char* lds, const Gemm g, const SchedT& S, const Epi& E, const int wid) {
;     ...
;         const bool has_next = S.next(ui + 1, nxt);
;         const char* nA = has_next ? (const char*)g.A + (size_t)nxt.pm * tstepA + (size_t)nxt.aoff * 2 : cA; const char* nB = has_next ? (const char*)g.Bt + (size_t)nxt.pn * tstepB + (size_t)nxt.boff * 2 : cB;
;         const int nt = cur.nt;
;         for (int t = 0; t < nt; t += 2) {
;             const bool last = (t == nt - 2);
;             const char* a1 = cA + (size_t)(t + 1) * kstep;
;             const char* a2 = last ? nA : cA + (size_t)(t + 2) * kstep; const char* b2 = last ? nB : cB + (size_t)(t + 2) * kstep;
;             const char* a3 = a2 + kstep; const char* b3 = b2 + kstep;
;     ...
; #pragma unroll
;         for (int a = 0; a < 2; ++a)
; #pragma unroll
;             for (int b = 0; b < 2; ++b)
; #pragma unroll
;                 for (int m = 0; m < 4; ++m)
; #pragma unroll
;                     for (int n = 0; n < 2; ++n) acc[a][b][m][n] = (f32x4){0.f, 0.f, 0.f, 0.f};
.LBB0_897:
	s_ashr_i32 s27, s26, 31
	s_lshl_b64 s[24:25], s[26:27], 19
	s_add_u32 s40, s2, s24
	s_addc_u32 s41, s3, s25
	s_ashr_i32 s15, s14, 31
	s_lshl_b64 s[24:25], s[14:15], 19
	s_add_u32 s42, s18, s24
	s_addc_u32 s43, s19, s25
	s_cmp_lt_i32 s20, 1
	s_cbranch_scc1 .LBB0_893
	v_cmp_lt_i64_e32 vcc, s[52:53], v[146:147]
	s_and_b64 s[24:25], vcc, exec
	s_cselect_b32 s15, s41, s49
	s_cselect_b32 s21, s40, s48
	s_cselect_b32 s24, s43, s51
	s_cselect_b32 s25, s42, s50
	s_add_i32 s27, s20, -2
	s_add_u32 s48, s48, 0x40080
	s_addc_u32 s49, s49, 0
	s_add_u32 s30, s50, 0x100
	v_mov_b32_e32 v0, 0
	s_addc_u32 s31, s51, 0
	s_mov_b32 s34, 0
	v_mov_b32_e32 v1, v0
	v_pk_mov_b32 v[2:3], v[0:1], v[0:1]
	v_pk_mov_b32 v[4:5], v[0:1], v[0:1]
	v_pk_mov_b32 v[6:7], v[0:1], v[0:1]
	v_pk_mov_b32 v[8:9], v[0:1], v[0:1]
	v_pk_mov_b32 v[10:11], v[0:1], v[0:1]
	v_pk_mov_b32 v[12:13], v[0:1], v[0:1]
	v_pk_mov_b32 v[14:15], v[0:1], v[0:1]
	v_pk_mov_b32 v[16:17], v[0:1], v[0:1]
	v_pk_mov_b32 v[18:19], v[0:1], v[0:1]
	v_pk_mov_b32 v[20:21], v[0:1], v[0:1]
	v_pk_mov_b32 v[22:23], v[0:1], v[0:1]
	v_pk_mov_b32 v[24:25], v[0:1], v[0:1]
	v_pk_mov_b32 v[26:27], v[0:1], v[0:1]
	v_pk_mov_b32 v[28:29], v[0:1], v[0:1]
	v_pk_mov_b32 v[30:31], v[0:1], v[0:1]
	v_pk_mov_b32 v[32:33], v[0:1], v[0:1]
	v_pk_mov_b32 v[34:35], v[0:1], v[0:1]
	v_pk_mov_b32 v[36:37], v[0:1], v[0:1]
	v_pk_mov_b32 v[38:39], v[0:1], v[0:1]
	v_pk_mov_b32 v[40:41], v[0:1], v[0:1]
	v_pk_mov_b32 v[42:43], v[0:1], v[0:1]
	v_pk_mov_b32 v[44:45], v[0:1], v[0:1]
	v_pk_mov_b32 v[46:47], v[0:1], v[0:1]
	v_pk_mov_b32 v[48:49], v[0:1], v[0:1]
	v_pk_mov_b32 v[50:51], v[0:1], v[0:1]
	v_pk_mov_b32 v[52:53], v[0:1], v[0:1]
	v_pk_mov_b32 v[54:55], v[0:1], v[0:1]
	v_pk_mov_b32 v[56:57], v[0:1], v[0:1]
	v_pk_mov_b32 v[58:59], v[0:1], v[0:1]
	v_pk_mov_b32 v[60:61], v[0:1], v[0:1]
	v_pk_mov_b32 v[62:63], v[0:1], v[0:1]
	v_pk_mov_b32 v[64:65], v[0:1], v[0:1]
	v_pk_mov_b32 v[66:67], v[0:1], v[0:1]
	v_pk_mov_b32 v[68:69], v[0:1], v[0:1]
	v_pk_mov_b32 v[70:71], v[0:1], v[0:1]
	v_pk_mov_b32 v[72:73], v[0:1], v[0:1]
	v_pk_mov_b32 v[74:75], v[0:1], v[0:1]
	v_pk_mov_b32 v[76:77], v[0:1], v[0:1]
	v_pk_mov_b32 v[78:79], v[0:1], v[0:1]
	v_pk_mov_b32 v[80:81], v[0:1], v[0:1]
	v_pk_mov_b32 v[82:83], v[0:1], v[0:1]
	v_pk_mov_b32 v[84:85], v[0:1], v[0:1]
	v_pk_mov_b32 v[86:87], v[0:1], v[0:1]
	v_pk_mov_b32 v[88:89], v[0:1], v[0:1]
	v_pk_mov_b32 v[90:91], v[0:1], v[0:1]
	v_pk_mov_b32 v[92:93], v[0:1], v[0:1]
	v_pk_mov_b32 v[94:95], v[0:1], v[0:1]
	v_pk_mov_b32 v[96:97], v[0:1], v[0:1]
	v_pk_mov_b32 v[98:99], v[0:1], v[0:1]
	v_pk_mov_b32 v[100:101], v[0:1], v[0:1]
	v_pk_mov_b32 v[102:103], v[0:1], v[0:1]
	v_pk_mov_b32 v[104:105], v[0:1], v[0:1]
	v_pk_mov_b32 v[106:107], v[0:1], v[0:1]
	v_pk_mov_b32 v[108:109], v[0:1], v[0:1]
	v_pk_mov_b32 v[110:111], v[0:1], v[0:1]
	v_pk_mov_b32 v[112:113], v[0:1], v[0:1]
	v_pk_mov_b32 v[114:115], v[0:1], v[0:1]
	v_pk_mov_b32 v[116:117], v[0:1], v[0:1]
	v_pk_mov_b32 v[118:119], v[0:1], v[0:1]
	v_pk_mov_b32 v[120:121], v[0:1], v[0:1]
	v_pk_mov_b32 v[122:123], v[0:1], v[0:1]
	v_pk_mov_b32 v[124:125], v[0:1], v[0:1]
	v_pk_mov_b32 v[126:127], v[0:1], v[0:1]

; template <class Epi, class SchedT, bool ALIGN_EPI, bool SP2, bool FP8 = false>
; __device__ __forceinline__ void gemm_phase(LAS unsigned char* lds, const Gemm g, const SchedT& S, const Epi& E, const int wid) {
;     ...
;         const bool has_next = S.next(ui + 1, nxt);
;         const char* nA = has_next ? (const char*)g.A + (size_t)nxt.pm * tstepA + (size_t)nxt.aoff * 2 : cA; const char* nB = has_next ? (const char*)g.Bt + (size_t)nxt.pn * tstepB + (size_t)nxt.boff * 2 : cB;
;         const int nt = cur.nt;
;         for (int t = 0; t < nt; t += 2) {
;             const bool last = (t == nt - 2);
;             const char* a1 = cA + (size_t)(t + 1) * kstep;
;             const char* a2 = last ? nA : cA + (size_t)(t + 2) * kstep; const char* b2 = last ? nB : cB + (size_t)(t + 2) * kstep;
;             const char* a3 = a2 + kstep; const char* b3 = b2 + kstep;
;     ...
; #pragma unroll
;         for (int a = 0; a < 2; ++a)
; #pragma unroll
;             for (int b = 0; b < 2; ++b)
; #pragma unroll
;                 for (int m = 0; m < 4; ++m)
; #pragma unroll
;                     for (int n = 0; n < 2; ++n) acc[a][b][m][n] = (f32x4){0.f, 0.f, 0.f, 0.f};
.LBB0_968:
	s_ashr_i32 s15, s14, 31
	s_lshl_b64 s[20:21], s[14:15], 21
	s_add_u32 s20, s36, s20
	s_addc_u32 s21, s37, s21
	s_ashr_i32 s13, s12, 31
	s_lshl_b64 s[22:23], s[12:13], 21
	s_add_u32 s22, s52, s22
	s_addc_u32 s23, s53, s23
	s_cmp_lt_i32 s30, 1
	s_cbranch_scc1 .LBB0_997
	s_and_b64 s[38:39], s[4:5], exec
	s_cselect_b32 s13, s21, s25
	s_cselect_b32 s15, s20, s24
	s_cselect_b32 s27, s23, s35
	s_cselect_b32 s31, s22, s34
	s_add_i32 s45, s30, -2
	s_add_u32 s24, s24, 0x100080
	s_addc_u32 s25, s25, 0
	s_add_u32 s46, s34, 0x100
	v_mov_b32_e32 v0, 0
	s_addc_u32 s47, s35, 0
	s_mov_b32 s34, 0
	v_mov_b32_e32 v1, v0
	v_pk_mov_b32 v[2:3], v[0:1], v[0:1]
	v_pk_mov_b32 v[4:5], v[0:1], v[0:1]
	v_pk_mov_b32 v[6:7], v[0:1], v[0:1]
	v_pk_mov_b32 v[8:9], v[0:1], v[0:1]
	v_pk_mov_b32 v[10:11], v[0:1], v[0:1]
	v_pk_mov_b32 v[12:13], v[0:1], v[0:1]
	v_pk_mov_b32 v[14:15], v[0:1], v[0:1]
	v_pk_mov_b32 v[16:17], v[0:1], v[0:1]
	v_pk_mov_b32 v[18:19], v[0:1], v[0:1]
	v_pk_mov_b32 v[20:21], v[0:1], v[0:1]
	v_pk_mov_b32 v[22:23], v[0:1], v[0:1]
	v_pk_mov_b32 v[24:25], v[0:1], v[0:1]
	v_pk_mov_b32 v[26:27], v[0:1], v[0:1]
	v_pk_mov_b32 v[28:29], v[0:1], v[0:1]
	v_pk_mov_b32 v[30:31], v[0:1], v[0:1]
	v_pk_mov_b32 v[32:33], v[0:1], v[0:1]
	v_pk_mov_b32 v[34:35], v[0:1], v[0:1]
	v_pk_mov_b32 v[36:37], v[0:1], v[0:1]
	v_pk_mov_b32 v[38:39], v[0:1], v[0:1]
	v_pk_mov_b32 v[40:41], v[0:1], v[0:1]
	v_pk_mov_b32 v[42:43], v[0:1], v[0:1]
	v_pk_mov_b32 v[44:45], v[0:1], v[0:1]
	v_pk_mov_b32 v[46:47], v[0:1], v[0:1]
	v_pk_mov_b32 v[48:49], v[0:1], v[0:1]
	v_pk_mov_b32 v[50:51], v[0:1], v[0:1]
	v_pk_mov_b32 v[52:53], v[0:1], v[0:1]
	v_pk_mov_b32 v[54:55], v[0:1], v[0:1]
	v_pk_mov_b32 v[56:57], v[0:1], v[0:1]
	v_pk_mov_b32 v[58:59], v[0:1], v[0:1]
	v_pk_mov_b32 v[60:61], v[0:1], v[0:1]
	v_pk_mov_b32 v[62:63], v[0:1], v[0:1]
	v_pk_mov_b32 v[64:65], v[0:1], v[0:1]
	v_pk_mov_b32 v[66:67], v[0:1], v[0:1]
	v_pk_mov_b32 v[68:69], v[0:1], v[0:1]
	v_pk_mov_b32 v[70:71], v[0:1], v[0:1]
	v_pk_mov_b32 v[72:73], v[0:1], v[0:1]
	v_pk_mov_b32 v[74:75], v[0:1], v[0:1]
	v_pk_mov_b32 v[76:77], v[0:1], v[0:1]
	v_pk_mov_b32 v[78:79], v[0:1], v[0:1]
	v_pk_mov_b32 v[80:81], v[0:1], v[0:1]
	v_pk_mov_b32 v[82:83], v[0:1], v[0:1]
	v_pk_mov_b32 v[84:85], v[0:1], v[0:1]
	v_pk_mov_b32 v[86:87], v[0:1], v[0:1]
	v_pk_mov_b32 v[88:89], v[0:1], v[0:1]
	v_pk_mov_b32 v[90:91], v[0:1], v[0:1]
	v_pk_mov_b32 v[92:93], v[0:1], v[0:1]
	v_pk_mov_b32 v[94:95], v[0:1], v[0:1]
	v_pk_mov_b32 v[96:97], v[0:1], v[0:1]
	v_pk_mov_b32 v[98:99], v[0:1], v[0:1]
	v_pk_mov_b32 v[100:101], v[0:1], v[0:1]
	v_pk_mov_b32 v[102:103], v[0:1], v[0:1]
	v_pk_mov_b32 v[104:105], v[0:1], v[0:1]
	v_pk_mov_b32 v[106:107], v[0:1], v[0:1]
	v_pk_mov_b32 v[108:109], v[0:1], v[0:1]
	v_pk_mov_b32 v[110:111], v[0:1], v[0:1]
	v_pk_mov_b32 v[112:113], v[0:1], v[0:1]
	v_pk_mov_b32 v[114:115], v[0:1], v[0:1]
	v_pk_mov_b32 v[116:117], v[0:1], v[0:1]
	v_pk_mov_b32 v[118:119], v[0:1], v[0:1]
	v_pk_mov_b32 v[120:121], v[0:1], v[0:1]
	v_pk_mov_b32 v[122:123], v[0:1], v[0:1]
	v_pk_mov_b32 v[124:125], v[0:1], v[0:1]
	v_pk_mov_b32 v[126:127], v[0:1], v[0:1]
